# stick-breaking item output: same whole-line store transpose as the MLA output (on top of v27)
# baseline (speedup 1.0000x reference)
; DI u32x2 pack4(const float* v) { u32x2 w; w.x = pk2(v[0], v[1]); w.y = pk2(v[2], v[3]); return w; }
; DI void sb_item(int g_wave, LAS unsigned char* lds, const bf16_t* SQ, const float* kf, const float* vf, bf16_t* MIX, int kvbase, int qrow0, int qpos0, int nq, int head,
;                 const float* ck, const float* cvp) {
;     ...
;     if (active) {
;         bf16_t* orow_ = MIX + (size_t)(qrow0 + 32 * w + r) * 1024 + 768 + head * 64;
; #pragma unroll
;         for (int g = 0; g < 4; ++g) {
;             float a[4], b[4];
; #pragma unroll
;             for (int j = 0; j < 4; ++j) { a[j] = o0[4 * g + j]; b[j] = o1[4 * g + j]; }
;             *(u32x2*)(orow_ + 8 * g + 4 * h) = pack4(a);
;             *(u32x2*)(orow_ + 32 + 8 * g + 4 * h) = pack4(b);
;         }
;     }
.LBB0_944:
	s_andn2_b64 vcc, exec, s[30:31]
	s_cbranch_vccnz .LBB0_946
	v_mbcnt_lo_u32_b32 v36, -1, 0
	v_mbcnt_hi_u32_b32 v36, -1, v36
	v_add_u32_e32 v32, s49, v106
	v_and_b32_e32 v37, 24, v36
	v_sub_u32_e32 v32, v32, v37
	v_ashrrev_i32_e32 v33, 31, v32
	v_lshlrev_b64 v[32:33], 11, v[32:33]
	v_lshl_add_u64 v[32:33], s[42:43], 0, v[32:33]
	s_lshl_b32 s92, s55, 1
	v_lshl_add_u64 v[32:33], v[32:33], 0, s[92:93]
	v_bfe_u32 v37, v36, 4, 1
	v_lshlrev_b32_e32 v37, 6, v37
	v_bfe_u32 v38, v36, 3, 1
	v_lshl_add_u32 v37, v38, 5, v37
	v_lshrrev_b32_e32 v38, 5, v36
	v_lshl_add_u32 v224, v38, 4, v37
	v_lshl_add_u64 v[32:33], v[32:33], 0, v[224:225]
	v_cvt_pk_bf16_f32 v0, v0, v1
	v_cvt_pk_bf16_f32 v1, v2, v3
	v_cvt_pk_bf16_f32 v2, v4, v5
	v_cvt_pk_bf16_f32 v3, v6, v7
	v_cvt_pk_bf16_f32 v4, v8, v9
	v_cvt_pk_bf16_f32 v5, v10, v11
	v_cvt_pk_bf16_f32 v6, v12, v13
	v_cvt_pk_bf16_f32 v7, v14, v15
	v_cvt_pk_bf16_f32 v8, v16, v17
	v_cvt_pk_bf16_f32 v9, v18, v19
	v_cvt_pk_bf16_f32 v10, v20, v21
	v_cvt_pk_bf16_f32 v11, v22, v23
	v_cvt_pk_bf16_f32 v12, v24, v25
	v_cvt_pk_bf16_f32 v13, v26, v27
	v_cvt_pk_bf16_f32 v14, v28, v29
	v_cvt_pk_bf16_f32 v15, v30, v31
	s_nop 1
	v_permlane32_swap_b32_e32 v0, v2
	v_permlane32_swap_b32_e32 v1, v3
	v_permlane32_swap_b32_e32 v4, v6
	v_permlane32_swap_b32_e32 v5, v7
	v_permlane32_swap_b32_e32 v8, v10
	v_permlane32_swap_b32_e32 v9, v11
	v_permlane32_swap_b32_e32 v12, v14
	v_permlane32_swap_b32_e32 v13, v15
	v_mov_b32_e32 v16, v4
	v_mov_b32_e32 v17, v5
	v_mov_b32_e32 v18, v6
	v_mov_b32_e32 v19, v7
	v_mov_b32_e32 v20, v12
	v_mov_b32_e32 v21, v13
	v_mov_b32_e32 v22, v14
	v_mov_b32_e32 v23, v15
	s_nop 1
	v_mov_b32_dpp v4, v0 row_ror:8 row_mask:0xf bank_mask:0x3
	v_mov_b32_dpp v5, v1 row_ror:8 row_mask:0xf bank_mask:0x3
	v_mov_b32_dpp v6, v2 row_ror:8 row_mask:0xf bank_mask:0x3
	v_mov_b32_dpp v7, v3 row_ror:8 row_mask:0xf bank_mask:0x3
	v_mov_b32_dpp v12, v8 row_ror:8 row_mask:0xf bank_mask:0x3
	v_mov_b32_dpp v13, v9 row_ror:8 row_mask:0xf bank_mask:0x3
	v_mov_b32_dpp v14, v10 row_ror:8 row_mask:0xf bank_mask:0x3
	v_mov_b32_dpp v15, v11 row_ror:8 row_mask:0xf bank_mask:0x3
	v_mov_b32_dpp v0, v16 row_ror:8 row_mask:0xf bank_mask:0xc
	v_mov_b32_dpp v1, v17 row_ror:8 row_mask:0xf bank_mask:0xc
	v_mov_b32_dpp v2, v18 row_ror:8 row_mask:0xf bank_mask:0xc
	v_mov_b32_dpp v3, v19 row_ror:8 row_mask:0xf bank_mask:0xc
	v_mov_b32_dpp v8, v20 row_ror:8 row_mask:0xf bank_mask:0xc
	v_mov_b32_dpp v9, v21 row_ror:8 row_mask:0xf bank_mask:0xc
	v_mov_b32_dpp v10, v22 row_ror:8 row_mask:0xf bank_mask:0xc
	v_mov_b32_dpp v11, v23 row_ror:8 row_mask:0xf bank_mask:0xc
	s_nop 1
	v_permlane16_swap_b32_e32 v0, v8
	v_permlane16_swap_b32_e32 v1, v9
	v_permlane16_swap_b32_e32 v2, v10
	v_permlane16_swap_b32_e32 v3, v11
	v_permlane16_swap_b32_e32 v4, v12
	v_permlane16_swap_b32_e32 v5, v13
	v_permlane16_swap_b32_e32 v6, v14
	v_permlane16_swap_b32_e32 v7, v15
	s_nop 1
	global_store_dwordx4 v[32:33], v[0:3], off offset:1536
	v_add_co_u32_e32 v32, vcc, 0x4000, v32
	s_nop 1
	v_addc_co_u32_e32 v33, vcc, 0, v33, vcc
	global_store_dwordx4 v[32:33], v[4:7], off offset:1536
	v_add_co_u32_e32 v32, vcc, 0x4000, v32
	s_nop 1
	v_addc_co_u32_e32 v33, vcc, 0, v33, vcc
	global_store_dwordx4 v[32:33], v[8:11], off offset:1536
	v_add_co_u32_e32 v32, vcc, 0x4000, v32
	s_nop 1
	v_addc_co_u32_e32 v33, vcc, 0, v33, vcc
	global_store_dwordx4 v[32:33], v[12:15], off offset:1536
